# phase-5 queue: next ticket requested at the barrier before a prompt ticket's last selection (late prefetch), on top of the ring-prefetch version
# baseline (speedup 1.0000x reference)
; #define PG8_LAS __attribute__((address_space(3)))
; __device__ __forceinline__ void mid1_phase(const Params& p, PG8_LAS unsigned char* lds) {
;     unsigned* ctr = (unsigned*)(p.ws + WS_CTR) + 64;
;     constexpr unsigned NA = DB, NB_ = MP / 8, NC_ = LRU_NGRP * 8, NB2 = NB_ / 2;
;     for (;;) {
.LBB0_861:
	s_cmp_lt_i32 s92, 6
	s_cselect_b64 s[0:1], -1, 0
	v_writelane_b32 v238, s0, 1
	s_nop 1
	v_writelane_b32 v238, s1, 2
	s_and_b64 s[0:1], s[0:1], s[4:5]
	s_andn2_b64 vcc, exec, s[0:1]
	s_cbranch_vccnz .LBB0_2814
	s_add_u32 s62, s34, 0x8100
	s_addc_u32 s63, s35, 0
	s_add_u32 s64, s34, 0x21dc0000
	s_addc_u32 s65, s35, 0
	s_add_u32 s66, s34, 0x22e40000
	v_writelane_b32 v239, s90, 60
	s_addc_u32 s67, s35, 0
	v_writelane_b32 v239, s92, 61
	s_add_u32 s0, s34, 0x340c6200
	v_mov_b32_e32 v99, 0
	v_writelane_b32 v238, s95, 0
	v_writelane_b32 v238, s0, 3
	s_addc_u32 s0, s35, 0
	v_writelane_b32 v238, s0, 4
	s_add_u32 s0, s34, 0x22e82000
	s_addc_u32 s1, s35, 0
	v_writelane_b32 v238, s0, 5
	v_writelane_b32 v239, s93, 62
	v_writelane_b32 v239, s94, 63
	v_writelane_b32 v238, s1, 6
	s_add_u32 s0, s34, 0x34046200
	v_writelane_b32 v238, s0, 7
	s_addc_u32 s0, s35, 0
	v_writelane_b32 v238, s0, 8
	s_add_u32 s0, s34, 0x34086200
	v_writelane_b32 v238, s0, 9
	s_addc_u32 s0, s35, 0
	s_add_u32 s70, s34, 0x25192000
	s_addc_u32 s71, s35, 0
	s_add_u32 s68, s34, 0x33f42200
	s_addc_u32 s69, s35, 0
	s_add_u32 s74, s34, 0x27212000
	s_addc_u32 s75, s35, 0
	s_add_u32 s60, s34, 0x33fc4200
	s_addc_u32 s61, s35, 0
	v_writelane_b32 v238, s0, 10
	s_add_u32 s0, s34, 0x1dbc0000
	s_addc_u32 s1, s35, 0
	v_writelane_b32 v238, s0, 11
	s_movk_i32 s81, 0x1000
	v_mov_b32_e32 v1, 0x3ecc95a3
	v_writelane_b32 v238, s1, 12
	s_add_u32 s0, s34, 0x3371a000
	v_writelane_b32 v238, s0, 13
	s_addc_u32 s0, s35, 0
	v_writelane_b32 v238, s0, 14
	s_add_u32 s0, s34, 0x22f0a000
	v_writelane_b32 v238, s0, 15
	s_addc_u32 s0, s35, 0
	v_writelane_b32 v238, s0, 16
	s_add_u32 s0, s34, 0x22e8a000
	v_writelane_b32 v238, s0, 17
	s_addc_u32 s0, s35, 0
	s_add_i32 s72, 0, 0x20c40
	v_writelane_b32 v238, s0, 18
	s_add_i32 s0, 0, 0x10000
	s_add_i32 s16, 0, 0x14400
	s_movk_i32 s17, 0x2000
	s_movk_i32 s78, 0xffc
	s_mov_b32 s79, 0x6390000
	s_mov_b32 s73, 0x6391000
	s_mov_b32 s76, 0x6392000
	s_mov_b32 s33, 0xbe800000
	v_mov_b32_e32 v101, 0x3d2aaaab
	v_mov_b32_e32 v156, s72
	v_mov_b32_e32 v157, 0x7f800000
	s_mov_b32 s93, 0
	s_mov_b64 s[94:95], 0x8000
	s_mov_b64 s[96:97], 0x2000
	v_writelane_b32 v238, s0, 19
	s_mov_b32 s98, 0
	s_branch .LBB0_867

; #define PG8_LAS __attribute__((address_space(3)))
; __device__ __forceinline__ unsigned wq_next(unsigned* ctr, PG8_LAS unsigned char* lds) {
;     volatile PG8_LAS unsigned* slot = (volatile PG8_LAS unsigned*)(lds + LDS_MISC + 64);
;     __syncthreads();
;     if (threadIdx.x == 0) *slot = atomicAdd(ctr, 1u);
;     __syncthreads();
;     return *slot;
; }
.LBB0_867:
	s_waitcnt vmcnt(0) lgkmcnt(0)
	s_barrier
	s_and_saveexec_b64 s[0:1], s[20:21]
	s_cbranch_execz .LBB0_871
	s_mov_b64 s[6:7], exec
	v_mbcnt_lo_u32_b32 v2, s6, 0
	v_mbcnt_hi_u32_b32 v2, s7, v2
	v_cmp_eq_u32_e32 vcc, 0, v2
	s_and_saveexec_b64 s[4:5], vcc
	s_cbranch_execz .LBB0_870
	s_bcnt1_i32_b64 s3, s[6:7]
	v_mov_b32_e32 v3, s3
	s_cmp_eq_u32 s98, 0
	s_cbranch_scc0 .Lwq5_pref
	global_atomic_add v3, v99, v3, s[62:63] sc0
	s_branch .LBB0_870
.Lwq5_pref:
	v_mov_b32_e32 v3, v240
.LBB0_870:
	s_or_b64 exec, exec, s[4:5]
	s_waitcnt vmcnt(0)
	v_readfirstlane_b32 s3, v3
	s_mov_b32 s98, 0
	v_mov_b32_e32 v3, s72
	s_nop 0
	v_add_u32_e32 v2, s3, v2
	ds_write_b32 v3, v2

; #define PG8_LAS __attribute__((address_space(3)))
; __device__ __forceinline__ unsigned fkey(float f) { const unsigned u = __float_as_uint(f); return (u & 0x80000000u) ? ~u : (u | 0x80000000u); }
;     constexpr int NG = (NJ + 7) / 8;
;     unsigned v[NJ];
;     const int nj = __builtin_amdgcn_readfirstlane((n + 63) >> 6), ng = (nj + 7) >> 3;
;     const PG8_LAS float* pl = sc + lane;
; #pragma unroll
;     for (int j = 0; j < NJ; ++j) { const unsigned k = fkey(pl[j * 64]); v[j] = (lane < n - j * 64) ? k : 0u; }
; __device__ __forceinline__ unsigned wq_next(unsigned* ctr, PG8_LAS unsigned char* lds) {
;     ...
;     if (threadIdx.x == 0) *slot = atomicAdd(ctr, 1u);
.LidxB_done:
.LBB0_1217:
	s_lshl_b32 s1, s0, 14
	s_add_i32 s1, s1, 0
	v_lshl_add_u32 v58, v84, 2, s1
	s_waitcnt lgkmcnt(0)
	s_barrier
	v_cmp_eq_u32_e32 vcc, 0, v0
	s_and_saveexec_b64 s[6:7], vcc
	v_mov_b32_e32 v241, 1
	global_atomic_add v240, v99, v241, s[62:63] sc0
	s_mov_b64 exec, s[6:7]
	s_mov_b32 s98, 1
	ds_read2st64_b32 v[4:5], v58 offset1:1
	s_add_i32 s4, s0, s10
	ds_read2st64_b32 v[6:7], v58 offset0:2 offset1:3
	ds_read2st64_b32 v[10:11], v58 offset0:4 offset1:5
	ds_read2st64_b32 v[12:13], v58 offset0:6 offset1:7
	s_sub_i32 s1, s4, 63
	s_add_i32 s3, s4, 0xffffff41
	s_waitcnt lgkmcnt(3)
	v_not_b32_e32 v2, v4
	v_or_b32_e32 v3, 0x80000000, v4
	v_cmp_gt_i32_e32 vcc, 0, v4
	v_or_b32_e32 v4, 0x80000000, v5
	s_waitcnt lgkmcnt(2)
	v_and_b32_e32 v9, 0x7fffffff, v6
	v_cndmask_b32_e32 v2, v3, v2, vcc
	v_cmp_ge_i32_e32 vcc, s4, v84
	v_and_b32_e32 v8, 0x7fffffff, v7
	v_pk_add_f32 v[8:9], v[8:9], 0 neg_lo:[1,1] neg_hi:[1,1]
	v_cndmask_b32_e32 v3, 0, v2, vcc
	v_not_b32_e32 v2, v5
	v_cmp_gt_i32_e32 vcc, 0, v5
	s_add_i32 s0, s4, 64
	s_ashr_i32 s5, s0, 6
	v_cndmask_b32_e32 v2, v4, v2, vcc
	v_cmp_gt_i32_e32 vcc, s1, v84
	v_xor_b32_e32 v4, -1, v7
	s_add_i32 s1, s4, 0xffffff81
	v_cndmask_b32_e32 v5, 0, v2, vcc
	v_cmp_gt_i32_e32 vcc, 0, v7
	v_xor_b32_e32 v2, -1, v6
	s_waitcnt lgkmcnt(1)
	v_and_b32_e32 v7, 0x7fffffff, v10
	v_cndmask_b32_e32 v4, v8, v4, vcc
	v_cmp_gt_i32_e32 vcc, 0, v6
	v_and_b32_e32 v6, 0x7fffffff, v11
	v_pk_add_f32 v[6:7], v[6:7], 0 neg_lo:[1,1] neg_hi:[1,1]
	v_cndmask_b32_e32 v2, v9, v2, vcc
	v_cmp_gt_i32_e32 vcc, s1, v84
	v_xor_b32_e32 v9, -1, v11
	s_add_i32 s1, s4, 0xffffff01
	v_cndmask_b32_e32 v8, 0, v2, vcc
	v_cmp_gt_i32_e32 vcc, s3, v84
	v_xor_b32_e32 v2, -1, v10
	s_add_i32 s3, s4, 0xfffffec1
	v_cndmask_b32_e32 v4, 0, v4, vcc
	v_cmp_gt_i32_e32 vcc, 0, v11
	s_waitcnt lgkmcnt(0)
	v_and_b32_e32 v11, 0x7fffffff, v12
	s_add_i32 s0, s5, 7
	v_cndmask_b32_e32 v6, v6, v9, vcc
	v_cmp_gt_i32_e32 vcc, 0, v10
	v_and_b32_e32 v10, 0x7fffffff, v13
	v_xor_b32_e32 v9, -1, v13
	v_cndmask_b32_e32 v2, v7, v2, vcc
	v_cmp_gt_i32_e32 vcc, s1, v84
	v_pk_add_f32 v[10:11], v[10:11], 0 neg_lo:[1,1] neg_hi:[1,1]
	s_add_i32 s1, s4, 0xfffffe81
	v_cndmask_b32_e32 v7, 0, v2, vcc
	v_cmp_gt_i32_e32 vcc, s3, v84
	s_add_i32 s3, s4, 0xfffffe41
	s_ashr_i32 s10, s0, 3
	v_cndmask_b32_e32 v2, 0, v6, vcc
	v_cmp_gt_i32_e32 vcc, 0, v13
	v_xor_b32_e32 v6, -1, v12
	s_nop 0
	v_cndmask_b32_e32 v13, v10, v9, vcc
	v_cmp_gt_i32_e32 vcc, 0, v12
	s_nop 1
	v_cndmask_b32_e32 v6, v11, v6, vcc
	ds_read2st64_b32 v[10:11], v58 offset0:8 offset1:9
	v_cmp_gt_i32_e32 vcc, s1, v84
	ds_read2st64_b32 v[14:15], v58 offset0:10 offset1:11
	ds_read2st64_b32 v[18:19], v58 offset0:12 offset1:13
	ds_read2st64_b32 v[20:21], v58 offset0:14 offset1:15
	v_cndmask_b32_e32 v9, 0, v6, vcc
	v_cmp_gt_i32_e32 vcc, s3, v84
	s_waitcnt lgkmcnt(3)
	v_and_b32_e32 v12, 0x7fffffff, v11
	v_xor_b32_e32 v17, -1, v11
	v_cndmask_b32_e32 v6, 0, v13, vcc
	v_and_b32_e32 v13, 0x7fffffff, v10
	v_pk_add_f32 v[12:13], v[12:13], 0 neg_lo:[1,1] neg_hi:[1,1]
	v_cmp_gt_i32_e32 vcc, 0, v11
	v_xor_b32_e32 v16, -1, v10
	s_add_i32 s1, s4, 0xfffffe01
	v_cndmask_b32_e32 v11, v12, v17, vcc
	v_cmp_gt_i32_e32 vcc, 0, v10
	s_add_i32 s3, s4, 0xfffffdc1
	s_waitcnt lgkmcnt(2)
	v_xor_b32_e32 v17, -1, v15
	v_cndmask_b32_e32 v10, v13, v16, vcc
	v_cmp_gt_i32_e32 vcc, s1, v84
	v_xor_b32_e32 v13, -1, v14
	s_add_i32 s1, s4, 0xfffffd81
	v_cndmask_b32_e32 v16, 0, v10, vcc
	v_cmp_gt_i32_e32 vcc, s3, v84
	v_and_b32_e32 v10, 0x7fffffff, v15
	s_add_i32 s3, s4, 0xfffffd41
	v_cndmask_b32_e32 v12, 0, v11, vcc
	v_and_b32_e32 v11, 0x7fffffff, v14
	v_pk_add_f32 v[10:11], v[10:11], 0 neg_lo:[1,1] neg_hi:[1,1]
	v_cmp_gt_i32_e32 vcc, 0, v15
	s_waitcnt lgkmcnt(1)
	v_and_b32_e32 v23, 0x7fffffff, v18
	v_and_b32_e32 v22, 0x7fffffff, v19
	v_cndmask_b32_e32 v10, v10, v17, vcc
	v_cmp_gt_i32_e32 vcc, 0, v14
	v_pk_add_f32 v[22:23], v[22:23], 0 neg_lo:[1,1] neg_hi:[1,1]
	s_waitcnt lgkmcnt(0)
	v_xor_b32_e32 v17, -1, v21
	v_cndmask_b32_e32 v11, v11, v13, vcc
	v_cmp_gt_i32_e32 vcc, s1, v84
	v_xor_b32_e32 v13, -1, v19
	s_add_i32 s1, s4, 0xfffffd01
	v_cndmask_b32_e32 v15, 0, v11, vcc
	v_cmp_gt_i32_e32 vcc, s3, v84
	s_add_i32 s3, s4, 0xfffffcc1
	s_nop 0
	v_cndmask_b32_e32 v11, 0, v10, vcc
	v_cmp_gt_i32_e32 vcc, 0, v19
	v_xor_b32_e32 v10, -1, v18
	v_and_b32_e32 v19, 0x7fffffff, v20
	v_cndmask_b32_e32 v13, v22, v13, vcc
	v_cmp_gt_i32_e32 vcc, 0, v18
	v_and_b32_e32 v18, 0x7fffffff, v21
	v_pk_add_f32 v[18:19], v[18:19], 0 neg_lo:[1,1] neg_hi:[1,1]
	v_cndmask_b32_e32 v10, v23, v10, vcc
	v_cmp_gt_i32_e32 vcc, s1, v84
	s_add_i32 s1, s4, 0xfffffc81
	s_nop 0
	v_cndmask_b32_e32 v14, 0, v10, vcc
	v_cmp_gt_i32_e32 vcc, s3, v84
	s_add_i32 s3, s4, 0xfffffc41
	s_nop 0
	v_cndmask_b32_e32 v10, 0, v13, vcc
	v_cmp_gt_i32_e32 vcc, 0, v21
	v_xor_b32_e32 v13, -1, v20
	s_nop 0
	v_cndmask_b32_e32 v21, v18, v17, vcc
	v_cmp_gt_i32_e32 vcc, 0, v20
	s_nop 1
	v_cndmask_b32_e32 v13, v19, v13, vcc
	ds_read2st64_b32 v[18:19], v58 offset0:16 offset1:17
	v_cmp_gt_i32_e32 vcc, s1, v84
	ds_read2st64_b32 v[22:23], v58 offset0:18 offset1:19
	ds_read2st64_b32 v[26:27], v58 offset0:20 offset1:21
	ds_read2st64_b32 v[28:29], v58 offset0:22 offset1:23
	v_cndmask_b32_e32 v17, 0, v13, vcc
	v_cmp_gt_i32_e32 vcc, s3, v84
	s_waitcnt lgkmcnt(3)
	v_and_b32_e32 v20, 0x7fffffff, v19
	v_xor_b32_e32 v25, -1, v19
	v_cndmask_b32_e32 v13, 0, v21, vcc
	v_and_b32_e32 v21, 0x7fffffff, v18
	v_pk_add_f32 v[20:21], v[20:21], 0 neg_lo:[1,1] neg_hi:[1,1]
	v_cmp_gt_i32_e32 vcc, 0, v19
	v_xor_b32_e32 v24, -1, v18
	s_add_i32 s1, s4, 0xfffffc01
	v_cndmask_b32_e32 v19, v20, v25, vcc
	v_cmp_gt_i32_e32 vcc, 0, v18
	s_add_i32 s3, s4, 0xfffffbc1
	s_waitcnt lgkmcnt(2)
; #define PG8_LAS __attribute__((address_space(3)))
; __device__ __forceinline__ unsigned fkey(float f) { const unsigned u = __float_as_uint(f); return (u & 0x80000000u) ? ~u : (u | 0x80000000u); }
;     ...
;     const int nj = __builtin_amdgcn_readfirstlane((n + 63) >> 6), ng = (nj + 7) >> 3;
;     const PG8_LAS float* pl = sc + lane;
; #pragma unroll
;     for (int j = 0; j < NJ; ++j) { const unsigned k = fkey(pl[j * 64]); v[j] = (lane < n - j * 64) ? k : 0u; }
	v_xor_b32_e32 v25, -1, v23
	v_cndmask_b32_e32 v18, v21, v24, vcc
	v_cmp_gt_i32_e32 vcc, s1, v84
	v_xor_b32_e32 v21, -1, v22
	s_add_i32 s1, s4, 0xfffffb81
	v_cndmask_b32_e32 v24, 0, v18, vcc
	v_cmp_gt_i32_e32 vcc, s3, v84
	v_and_b32_e32 v18, 0x7fffffff, v23
	s_add_i32 s3, s4, 0xfffffb41
	v_cndmask_b32_e32 v20, 0, v19, vcc
	v_and_b32_e32 v19, 0x7fffffff, v22
	v_pk_add_f32 v[18:19], v[18:19], 0 neg_lo:[1,1] neg_hi:[1,1]
	v_cmp_gt_i32_e32 vcc, 0, v23
	s_waitcnt lgkmcnt(1)
	v_and_b32_e32 v31, 0x7fffffff, v26
	v_and_b32_e32 v30, 0x7fffffff, v27
	v_cndmask_b32_e32 v18, v18, v25, vcc
	v_cmp_gt_i32_e32 vcc, 0, v22
	v_pk_add_f32 v[30:31], v[30:31], 0 neg_lo:[1,1] neg_hi:[1,1]
	s_waitcnt lgkmcnt(0)
	v_xor_b32_e32 v25, -1, v29
	v_cndmask_b32_e32 v19, v19, v21, vcc
	v_cmp_gt_i32_e32 vcc, s1, v84
	v_xor_b32_e32 v21, -1, v27
	s_add_i32 s1, s4, 0xfffffb01
	v_cndmask_b32_e32 v23, 0, v19, vcc
	v_cmp_gt_i32_e32 vcc, s3, v84
	s_add_i32 s3, s4, 0xfffffac1
	s_nop 0
	v_cndmask_b32_e32 v19, 0, v18, vcc
	v_cmp_gt_i32_e32 vcc, 0, v27
	v_xor_b32_e32 v18, -1, v26
	v_and_b32_e32 v27, 0x7fffffff, v28
	v_cndmask_b32_e32 v21, v30, v21, vcc
	v_cmp_gt_i32_e32 vcc, 0, v26
	v_and_b32_e32 v26, 0x7fffffff, v29
	v_pk_add_f32 v[26:27], v[26:27], 0 neg_lo:[1,1] neg_hi:[1,1]
	v_cndmask_b32_e32 v18, v31, v18, vcc
	v_cmp_gt_i32_e32 vcc, s1, v84
	s_add_i32 s1, s4, 0xfffffa81
	s_nop 0
	v_cndmask_b32_e32 v22, 0, v18, vcc
	v_cmp_gt_i32_e32 vcc, s3, v84
	s_add_i32 s3, s4, 0xfffffa41
	s_nop 0
	v_cndmask_b32_e32 v18, 0, v21, vcc
	v_cmp_gt_i32_e32 vcc, 0, v29
	v_xor_b32_e32 v21, -1, v28
	s_nop 0
	v_cndmask_b32_e32 v29, v26, v25, vcc
	v_cmp_gt_i32_e32 vcc, 0, v28
	s_nop 1
	v_cndmask_b32_e32 v21, v27, v21, vcc
	ds_read2st64_b32 v[26:27], v58 offset0:24 offset1:25
	v_cmp_gt_i32_e32 vcc, s1, v84
	ds_read2st64_b32 v[30:31], v58 offset0:26 offset1:27
	ds_read2st64_b32 v[34:35], v58 offset0:28 offset1:29
	ds_read2st64_b32 v[36:37], v58 offset0:30 offset1:31
	v_cndmask_b32_e32 v25, 0, v21, vcc
	v_cmp_gt_i32_e32 vcc, s3, v84
	s_waitcnt lgkmcnt(3)
	v_and_b32_e32 v28, 0x7fffffff, v27
	v_xor_b32_e32 v33, -1, v27
	v_cndmask_b32_e32 v21, 0, v29, vcc
	v_and_b32_e32 v29, 0x7fffffff, v26
	v_pk_add_f32 v[28:29], v[28:29], 0 neg_lo:[1,1] neg_hi:[1,1]
	v_cmp_gt_i32_e32 vcc, 0, v27
	v_xor_b32_e32 v32, -1, v26
	s_add_i32 s1, s4, 0xfffffa01
	v_cndmask_b32_e32 v27, v28, v33, vcc
	v_cmp_gt_i32_e32 vcc, 0, v26
	s_add_i32 s3, s4, 0xfffff9c1
	s_waitcnt lgkmcnt(2)
	v_xor_b32_e32 v33, -1, v31
	v_cndmask_b32_e32 v26, v29, v32, vcc
	v_cmp_gt_i32_e32 vcc, s1, v84
	v_xor_b32_e32 v29, -1, v30
	s_add_i32 s1, s4, 0xfffff981
	v_cndmask_b32_e32 v32, 0, v26, vcc
	v_cmp_gt_i32_e32 vcc, s3, v84
	v_and_b32_e32 v26, 0x7fffffff, v31
	s_add_i32 s3, s4, 0xfffff941
	v_cndmask_b32_e32 v28, 0, v27, vcc
	v_and_b32_e32 v27, 0x7fffffff, v30
	v_pk_add_f32 v[26:27], v[26:27], 0 neg_lo:[1,1] neg_hi:[1,1]
	v_cmp_gt_i32_e32 vcc, 0, v31
	s_waitcnt lgkmcnt(1)
	v_and_b32_e32 v39, 0x7fffffff, v34
	v_and_b32_e32 v38, 0x7fffffff, v35
	v_cndmask_b32_e32 v26, v26, v33, vcc
	v_cmp_gt_i32_e32 vcc, 0, v30
	v_pk_add_f32 v[38:39], v[38:39], 0 neg_lo:[1,1] neg_hi:[1,1]
	s_waitcnt lgkmcnt(0)
	v_xor_b32_e32 v33, -1, v37
	v_cndmask_b32_e32 v27, v27, v29, vcc
	v_cmp_gt_i32_e32 vcc, s1, v84
	v_xor_b32_e32 v29, -1, v35
	s_add_i32 s1, s4, 0xfffff901
	v_cndmask_b32_e32 v31, 0, v27, vcc
	v_cmp_gt_i32_e32 vcc, s3, v84
	s_add_i32 s3, s4, 0xfffff8c1
	s_nop 0
	v_cndmask_b32_e32 v27, 0, v26, vcc
	v_cmp_gt_i32_e32 vcc, 0, v35
	v_xor_b32_e32 v26, -1, v34
	v_and_b32_e32 v35, 0x7fffffff, v36
	v_cndmask_b32_e32 v29, v38, v29, vcc
	v_cmp_gt_i32_e32 vcc, 0, v34
	v_and_b32_e32 v34, 0x7fffffff, v37
	v_pk_add_f32 v[34:35], v[34:35], 0 neg_lo:[1,1] neg_hi:[1,1]
	v_cndmask_b32_e32 v26, v39, v26, vcc
	v_cmp_gt_i32_e32 vcc, s1, v84
	s_add_i32 s1, s4, 0xfffff881
	s_nop 0
	v_cndmask_b32_e32 v30, 0, v26, vcc
	v_cmp_gt_i32_e32 vcc, s3, v84
	s_add_i32 s3, s4, 0xfffff841
	s_nop 0
	v_cndmask_b32_e32 v26, 0, v29, vcc
	v_cmp_gt_i32_e32 vcc, 0, v37
	v_xor_b32_e32 v29, -1, v36
	s_nop 0
	v_cndmask_b32_e32 v37, v34, v33, vcc
	v_cmp_gt_i32_e32 vcc, 0, v36
	s_nop 1
	v_cndmask_b32_e32 v29, v35, v29, vcc
	ds_read2st64_b32 v[34:35], v58 offset0:32 offset1:33
	v_cmp_gt_i32_e32 vcc, s1, v84
	ds_read2st64_b32 v[38:39], v58 offset0:34 offset1:35
	ds_read2st64_b32 v[42:43], v58 offset0:36 offset1:37
	ds_read2st64_b32 v[44:45], v58 offset0:38 offset1:39
	v_cndmask_b32_e32 v33, 0, v29, vcc
	v_cmp_gt_i32_e32 vcc, s3, v84
	s_waitcnt lgkmcnt(3)
	v_and_b32_e32 v36, 0x7fffffff, v35
	v_xor_b32_e32 v41, -1, v35
	v_cndmask_b32_e32 v29, 0, v37, vcc
	v_and_b32_e32 v37, 0x7fffffff, v34
	v_pk_add_f32 v[36:37], v[36:37], 0 neg_lo:[1,1] neg_hi:[1,1]
	v_cmp_gt_i32_e32 vcc, 0, v35
	v_xor_b32_e32 v40, -1, v34
	s_add_i32 s1, s4, 0xfffff801
	v_cndmask_b32_e32 v35, v36, v41, vcc
	v_cmp_gt_i32_e32 vcc, 0, v34
	s_add_i32 s3, s4, 0xfffff7c1
	s_waitcnt lgkmcnt(2)
	v_xor_b32_e32 v41, -1, v39
	v_cndmask_b32_e32 v34, v37, v40, vcc
	v_cmp_gt_i32_e32 vcc, s1, v84
	v_xor_b32_e32 v37, -1, v38
	s_add_i32 s1, s4, 0xfffff781
	v_cndmask_b32_e32 v40, 0, v34, vcc
	v_cmp_gt_i32_e32 vcc, s3, v84
	v_and_b32_e32 v34, 0x7fffffff, v39
	s_add_i32 s3, s4, 0xfffff741
	v_cndmask_b32_e32 v36, 0, v35, vcc
	v_and_b32_e32 v35, 0x7fffffff, v38
	v_pk_add_f32 v[34:35], v[34:35], 0 neg_lo:[1,1] neg_hi:[1,1]
	v_cmp_gt_i32_e32 vcc, 0, v39
	s_waitcnt lgkmcnt(1)
	v_and_b32_e32 v47, 0x7fffffff, v42
	v_and_b32_e32 v46, 0x7fffffff, v43
	v_cndmask_b32_e32 v34, v34, v41, vcc
	v_cmp_gt_i32_e32 vcc, 0, v38
	v_pk_add_f32 v[46:47], v[46:47], 0 neg_lo:[1,1] neg_hi:[1,1]
	s_waitcnt lgkmcnt(0)
; #define PG8_LAS __attribute__((address_space(3)))
; __device__ __forceinline__ unsigned fkey(float f) { const unsigned u = __float_as_uint(f); return (u & 0x80000000u) ? ~u : (u | 0x80000000u); }
;     ...
;     const int nj = __builtin_amdgcn_readfirstlane((n + 63) >> 6), ng = (nj + 7) >> 3;
;     const PG8_LAS float* pl = sc + lane;
; #pragma unroll
;     for (int j = 0; j < NJ; ++j) { const unsigned k = fkey(pl[j * 64]); v[j] = (lane < n - j * 64) ? k : 0u; }
	v_xor_b32_e32 v41, -1, v45
	v_cndmask_b32_e32 v35, v35, v37, vcc
	v_cmp_gt_i32_e32 vcc, s1, v84
	v_xor_b32_e32 v37, -1, v43
	s_add_i32 s1, s4, 0xfffff701
	v_cndmask_b32_e32 v39, 0, v35, vcc
	v_cmp_gt_i32_e32 vcc, s3, v84
	s_add_i32 s3, s4, 0xfffff6c1
	s_nop 0
	v_cndmask_b32_e32 v35, 0, v34, vcc
	v_cmp_gt_i32_e32 vcc, 0, v43
	v_xor_b32_e32 v34, -1, v42
	v_and_b32_e32 v43, 0x7fffffff, v44
	v_cndmask_b32_e32 v37, v46, v37, vcc
	v_cmp_gt_i32_e32 vcc, 0, v42
	v_and_b32_e32 v42, 0x7fffffff, v45
	v_pk_add_f32 v[42:43], v[42:43], 0 neg_lo:[1,1] neg_hi:[1,1]
	v_cndmask_b32_e32 v34, v47, v34, vcc
	v_cmp_gt_i32_e32 vcc, s1, v84
	s_add_i32 s1, s4, 0xfffff681
	s_nop 0
	v_cndmask_b32_e32 v38, 0, v34, vcc
	v_cmp_gt_i32_e32 vcc, s3, v84
	s_add_i32 s3, s4, 0xfffff641
	s_nop 0
	v_cndmask_b32_e32 v34, 0, v37, vcc
	v_cmp_gt_i32_e32 vcc, 0, v45
	v_xor_b32_e32 v37, -1, v44
	s_nop 0
	v_cndmask_b32_e32 v45, v42, v41, vcc
	v_cmp_gt_i32_e32 vcc, 0, v44
	s_nop 1
	v_cndmask_b32_e32 v37, v43, v37, vcc
	ds_read2st64_b32 v[42:43], v58 offset0:40 offset1:41
	v_cmp_gt_i32_e32 vcc, s1, v84
	ds_read2st64_b32 v[46:47], v58 offset0:42 offset1:43
	ds_read2st64_b32 v[50:51], v58 offset0:44 offset1:45
	ds_read2st64_b32 v[52:53], v58 offset0:46 offset1:47
	v_cndmask_b32_e32 v41, 0, v37, vcc
	v_cmp_gt_i32_e32 vcc, s3, v84
	s_waitcnt lgkmcnt(3)
	v_and_b32_e32 v44, 0x7fffffff, v43
	v_xor_b32_e32 v49, -1, v43
	v_cndmask_b32_e32 v37, 0, v45, vcc
	v_and_b32_e32 v45, 0x7fffffff, v42
	v_pk_add_f32 v[44:45], v[44:45], 0 neg_lo:[1,1] neg_hi:[1,1]
	v_cmp_gt_i32_e32 vcc, 0, v43
	v_xor_b32_e32 v48, -1, v42
	s_add_i32 s1, s4, 0xfffff601
	v_cndmask_b32_e32 v43, v44, v49, vcc
	v_cmp_gt_i32_e32 vcc, 0, v42
	s_add_i32 s3, s4, 0xfffff5c1
	s_waitcnt lgkmcnt(2)
	v_xor_b32_e32 v49, -1, v47
	v_cndmask_b32_e32 v42, v45, v48, vcc
	v_cmp_gt_i32_e32 vcc, s1, v84
	v_xor_b32_e32 v45, -1, v46
	s_add_i32 s1, s4, 0xfffff581
	v_cndmask_b32_e32 v48, 0, v42, vcc
	v_cmp_gt_i32_e32 vcc, s3, v84
	v_and_b32_e32 v42, 0x7fffffff, v47
	s_add_i32 s3, s4, 0xfffff541
	v_cndmask_b32_e32 v44, 0, v43, vcc
	v_and_b32_e32 v43, 0x7fffffff, v46
	v_pk_add_f32 v[42:43], v[42:43], 0 neg_lo:[1,1] neg_hi:[1,1]
	v_cmp_gt_i32_e32 vcc, 0, v47
	s_waitcnt lgkmcnt(1)
	v_and_b32_e32 v55, 0x7fffffff, v50
	v_and_b32_e32 v54, 0x7fffffff, v51
	v_cndmask_b32_e32 v42, v42, v49, vcc
	v_cmp_gt_i32_e32 vcc, 0, v46
	v_pk_add_f32 v[54:55], v[54:55], 0 neg_lo:[1,1] neg_hi:[1,1]
	s_waitcnt lgkmcnt(0)
	v_xor_b32_e32 v49, -1, v53
	v_cndmask_b32_e32 v43, v43, v45, vcc
	v_cmp_gt_i32_e32 vcc, s1, v84
	v_xor_b32_e32 v45, -1, v51
	s_add_i32 s1, s4, 0xfffff501
	v_cndmask_b32_e32 v47, 0, v43, vcc
	v_cmp_gt_i32_e32 vcc, s3, v84
	s_add_i32 s3, s4, 0xfffff4c1
	s_nop 0
	v_cndmask_b32_e32 v43, 0, v42, vcc
	v_cmp_gt_i32_e32 vcc, 0, v51
	v_xor_b32_e32 v42, -1, v50
	v_and_b32_e32 v51, 0x7fffffff, v52
	v_cndmask_b32_e32 v45, v54, v45, vcc
	v_cmp_gt_i32_e32 vcc, 0, v50
	v_and_b32_e32 v50, 0x7fffffff, v53
	v_pk_add_f32 v[50:51], v[50:51], 0 neg_lo:[1,1] neg_hi:[1,1]
	v_cndmask_b32_e32 v42, v55, v42, vcc
	v_cmp_gt_i32_e32 vcc, s1, v84
	s_add_i32 s1, s4, 0xfffff481
	s_nop 0
	v_cndmask_b32_e32 v46, 0, v42, vcc
	v_cmp_gt_i32_e32 vcc, s3, v84
	s_add_i32 s3, s4, 0xfffff441
	s_nop 0
	v_cndmask_b32_e32 v42, 0, v45, vcc
	v_cmp_gt_i32_e32 vcc, 0, v53
	v_xor_b32_e32 v45, -1, v52
	s_nop 0
	v_cndmask_b32_e32 v53, v50, v49, vcc
	v_cmp_gt_i32_e32 vcc, 0, v52
	s_nop 1
	v_cndmask_b32_e32 v45, v51, v45, vcc
	ds_read2st64_b32 v[50:51], v58 offset0:48 offset1:49
	v_cmp_gt_i32_e32 vcc, s1, v84
	ds_read2st64_b32 v[54:55], v58 offset0:50 offset1:51
	ds_read2st64_b32 v[60:61], v58 offset0:52 offset1:53
	ds_read2st64_b32 v[62:63], v58 offset0:54 offset1:55
	v_cndmask_b32_e32 v49, 0, v45, vcc
	v_cmp_gt_i32_e32 vcc, s3, v84
	s_waitcnt lgkmcnt(3)
	v_and_b32_e32 v52, 0x7fffffff, v51
	v_xor_b32_e32 v57, -1, v51
	v_cndmask_b32_e32 v45, 0, v53, vcc
	v_and_b32_e32 v53, 0x7fffffff, v50
	v_pk_add_f32 v[52:53], v[52:53], 0 neg_lo:[1,1] neg_hi:[1,1]
	v_cmp_gt_i32_e32 vcc, 0, v51
	v_xor_b32_e32 v56, -1, v50
	s_add_i32 s1, s4, 0xfffff401
	v_cndmask_b32_e32 v51, v52, v57, vcc
	v_cmp_gt_i32_e32 vcc, 0, v50
	s_add_i32 s3, s4, 0xfffff3c1
	s_waitcnt lgkmcnt(2)
	v_xor_b32_e32 v57, -1, v55
	v_cndmask_b32_e32 v50, v53, v56, vcc
	v_cmp_gt_i32_e32 vcc, s1, v84
	v_xor_b32_e32 v53, -1, v54
	s_add_i32 s1, s4, 0xfffff381
	v_cndmask_b32_e32 v56, 0, v50, vcc
	v_cmp_gt_i32_e32 vcc, s3, v84
	v_and_b32_e32 v50, 0x7fffffff, v55
	s_add_i32 s3, s4, 0xfffff341
	v_cndmask_b32_e32 v52, 0, v51, vcc
	v_and_b32_e32 v51, 0x7fffffff, v54
	v_pk_add_f32 v[50:51], v[50:51], 0 neg_lo:[1,1] neg_hi:[1,1]
	v_cmp_gt_i32_e32 vcc, 0, v55
	s_waitcnt lgkmcnt(1)
; __device__ __forceinline__ unsigned fkey(float f) { const unsigned u = __float_as_uint(f); return (u & 0x80000000u) ? ~u : (u | 0x80000000u); }
;     ...
;     for (int j = 0; j < NJ; ++j) { const unsigned k = fkey(pl[j * 64]); v[j] = (lane < n - j * 64) ? k : 0u; }
;     unsigned T = 1u; int need = 1 << 30;
;     if (n > TOPK) {
;         unsigned prefix = 0u; bool exact;
;         if (NG >= 8 && ng > 7) exact = bit_search<(NG >= 8 ? 8 : NG), NJ, BITLO>(v, prefix);
;         else if (NG >= 7 && ng > 6) exact = bit_search<(NG >= 7 ? 7 : NG), NJ, BITLO>(v, prefix);
;         else if (NG >= 6 && ng > 5) exact = bit_search<(NG >= 6 ? 6 : NG), NJ, BITLO>(v, prefix);
;         else if (NG >= 5 && ng > 4) exact = bit_search<(NG >= 5 ? 5 : NG), NJ, BITLO>(v, prefix);
;         else if (NG >= 4 && ng > 3) exact = bit_search<(NG >= 4 ? 4 : NG), NJ, BITLO>(v, prefix);
;         else if (NG >= 3 && ng > 2) exact = bit_search<(NG >= 3 ? 3 : NG), NJ, BITLO>(v, prefix);
;         else if (NG >= 2 && ng > 1) exact = bit_search<(NG >= 2 ? 2 : NG), NJ, BITLO>(v, prefix);
;         else exact = bit_search<1, NJ, BITLO>(v, prefix);
	v_and_b32_e32 v65, 0x7fffffff, v60
	v_and_b32_e32 v64, 0x7fffffff, v61
	v_cndmask_b32_e32 v50, v50, v57, vcc
	v_cmp_gt_i32_e32 vcc, 0, v54
	v_pk_add_f32 v[64:65], v[64:65], 0 neg_lo:[1,1] neg_hi:[1,1]
	s_waitcnt lgkmcnt(0)
	v_xor_b32_e32 v57, -1, v63
	v_cndmask_b32_e32 v51, v51, v53, vcc
	v_cmp_gt_i32_e32 vcc, s1, v84
	v_xor_b32_e32 v53, -1, v61
	s_add_i32 s1, s4, 0xfffff301
	v_cndmask_b32_e32 v55, 0, v51, vcc
	v_cmp_gt_i32_e32 vcc, s3, v84
	s_add_i32 s3, s4, 0xfffff2c1
	s_nop 0
	v_cndmask_b32_e32 v51, 0, v50, vcc
	v_cmp_gt_i32_e32 vcc, 0, v61
	v_xor_b32_e32 v50, -1, v60
	v_and_b32_e32 v61, 0x7fffffff, v62
	v_cndmask_b32_e32 v53, v64, v53, vcc
	v_cmp_gt_i32_e32 vcc, 0, v60
	v_and_b32_e32 v60, 0x7fffffff, v63
	v_pk_add_f32 v[60:61], v[60:61], 0 neg_lo:[1,1] neg_hi:[1,1]
	v_cndmask_b32_e32 v50, v65, v50, vcc
	v_cmp_gt_i32_e32 vcc, s1, v84
	s_add_i32 s1, s4, 0xfffff281
	s_nop 0
	v_cndmask_b32_e32 v54, 0, v50, vcc
	v_cmp_gt_i32_e32 vcc, s3, v84
	s_add_i32 s3, s4, 0xfffff241
	s_nop 0
	v_cndmask_b32_e32 v50, 0, v53, vcc
	v_cmp_gt_i32_e32 vcc, 0, v63
	v_xor_b32_e32 v53, -1, v62
	s_nop 0
	v_cndmask_b32_e32 v59, v60, v57, vcc
	v_cmp_gt_i32_e32 vcc, 0, v62
	s_nop 1
	v_cndmask_b32_e32 v53, v61, v53, vcc
	ds_read2st64_b32 v[60:61], v58 offset0:56 offset1:57
	v_cmp_gt_i32_e32 vcc, s1, v84
	ds_read2st64_b32 v[62:63], v58 offset0:58 offset1:59
	ds_read2st64_b32 v[66:67], v58 offset0:60 offset1:61
	ds_read2st64_b32 v[68:69], v58 offset0:62 offset1:63
	v_cndmask_b32_e32 v57, 0, v53, vcc
	v_cmp_gt_i32_e32 vcc, s3, v84
	s_waitcnt lgkmcnt(3)
	v_and_b32_e32 v58, 0x7fffffff, v61
	v_xor_b32_e32 v65, -1, v61
	v_cndmask_b32_e32 v53, 0, v59, vcc
	v_and_b32_e32 v59, 0x7fffffff, v60
	v_pk_add_f32 v[58:59], v[58:59], 0 neg_lo:[1,1] neg_hi:[1,1]
	v_cmp_gt_i32_e32 vcc, 0, v61
	v_xor_b32_e32 v64, -1, v60
	s_add_i32 s1, s4, 0xfffff201
	v_cndmask_b32_e32 v58, v58, v65, vcc
	v_cmp_gt_i32_e32 vcc, 0, v60
	s_add_i32 s3, s4, 0xfffff1c1
	s_waitcnt lgkmcnt(2)
	v_xor_b32_e32 v65, -1, v63
	v_cndmask_b32_e32 v59, v59, v64, vcc
	v_cmp_gt_i32_e32 vcc, s1, v84
	v_xor_b32_e32 v61, -1, v62
	s_add_i32 s1, s4, 0xfffff181
	v_cndmask_b32_e32 v64, 0, v59, vcc
	v_cmp_gt_i32_e32 vcc, s3, v84
	v_and_b32_e32 v59, 0x7fffffff, v62
	s_add_i32 s3, s4, 0xfffff141
	v_cndmask_b32_e32 v60, 0, v58, vcc
	v_and_b32_e32 v58, 0x7fffffff, v63
	v_pk_add_f32 v[58:59], v[58:59], 0 neg_lo:[1,1] neg_hi:[1,1]
	v_cmp_gt_i32_e32 vcc, 0, v63
	s_waitcnt lgkmcnt(1)
	v_and_b32_e32 v71, 0x7fffffff, v66
	v_and_b32_e32 v70, 0x7fffffff, v67
	v_cndmask_b32_e32 v58, v58, v65, vcc
	v_cmp_gt_i32_e32 vcc, 0, v62
	v_pk_add_f32 v[70:71], v[70:71], 0 neg_lo:[1,1] neg_hi:[1,1]
	s_waitcnt lgkmcnt(0)
	v_xor_b32_e32 v65, -1, v69
	v_cndmask_b32_e32 v59, v59, v61, vcc
	v_cmp_gt_i32_e32 vcc, s1, v84
	v_xor_b32_e32 v61, -1, v67
	s_add_i32 s1, s4, 0xfffff101
	v_cndmask_b32_e32 v63, 0, v59, vcc
	v_cmp_gt_i32_e32 vcc, s3, v84
	s_add_i32 s3, s4, 0xfffff0c1
	s_nop 0
	v_cndmask_b32_e32 v59, 0, v58, vcc
	v_cmp_gt_i32_e32 vcc, 0, v67
	v_xor_b32_e32 v58, -1, v66
	v_and_b32_e32 v67, 0x7fffffff, v68
	v_cndmask_b32_e32 v62, v70, v61, vcc
	v_cmp_gt_i32_e32 vcc, 0, v66
	v_and_b32_e32 v66, 0x7fffffff, v69
	v_pk_add_f32 v[66:67], v[66:67], 0 neg_lo:[1,1] neg_hi:[1,1]
	v_cndmask_b32_e32 v58, v71, v58, vcc
	v_cmp_gt_i32_e32 vcc, s1, v84
	s_add_i32 s1, s4, 0xfffff081
	s_nop 0
	v_cndmask_b32_e32 v61, 0, v58, vcc
	v_cmp_gt_i32_e32 vcc, s3, v84
	s_add_i32 s3, s4, 0xfffff041
	s_cmpk_lt_i32 s4, 0x100
	v_cndmask_b32_e32 v58, 0, v62, vcc
	v_cmp_gt_i32_e32 vcc, 0, v69
	v_xor_b32_e32 v62, -1, v68
	s_nop 0
	v_cndmask_b32_e32 v66, v66, v65, vcc
	v_cmp_gt_i32_e32 vcc, 0, v68
	s_nop 1
	v_cndmask_b32_e32 v62, v67, v62, vcc
	v_cmp_gt_i32_e32 vcc, s1, v84
	s_nop 1
	v_cndmask_b32_e32 v65, 0, v62, vcc
	v_cmp_gt_i32_e32 vcc, s3, v84
	s_nop 1
	v_cndmask_b32_e32 v62, 0, v66, vcc
	s_cbranch_scc1 .LBB0_1228
	s_cmp_gt_i32 s10, 7
	s_cselect_b64 s[0:1], -1, 0
	s_cmp_lt_i32 s10, 8
	s_cbranch_scc0 .LBB0_1229
	s_cmp_lg_u32 s10, 7
	s_cbranch_scc0 .LBB0_1231
	s_cmp_lt_i32 s10, 6
	s_cbranch_scc0 .LBB0_1233
	s_cmp_lg_u32 s10, 5
	s_cbranch_scc0 .LBB0_1234
	s_cmp_lt_i32 s10, 4
	s_cbranch_scc0 .LBB0_1235
	s_cmp_lg_u32 s10, 3
	s_cbranch_scc0 .LBB0_1236
	s_cmp_gt_i32 s10, 1
	s_cbranch_scc1 .LBB0_1237
	v_mov_b32_e32 v67, 31
	v_mov_b32_e32 v66, 0
